# code placement: all hot loop heads (GEMM K-loops, diff main, dil, gate loops, scan loops) pinned to 64B with .p2align 6 (stacked on v17)
# speedup vs baseline: 1.0033x; 1.0033x over previous
; #define LAS __attribute__((address_space(3)))
; DI void gla_gate_phase(int wv, LAS unsigned char* lds, const float* x, const float* w_in, const float* w2, const float* bg, const bf16_t* qk1,
;                        bf16_t* qd, bf16_t* ki, bf16_t* kst, float* decay, bf16_t* sbuf) {
;     ...
;         for (int tt = 0; tt < 8; tt += 2) {
;             const size_t t0 = T0 + wid * 8 + tt;
;             float a0[16], a1[16];
; #pragma unroll
;             for (int n = 0; n < 16; ++n) { a0[n] = 0.f; a1[n] = 0.f; }
; #pragma unroll
;             for (int i = 0; i < 16; ++i) { const int k = lane + 64 * i; const float x0 = x[t0 * DM + k], x1 = x[(t0 + 1) * DM + k];
; #pragma unroll
;                 for (int q = 0; q < 4; ++q) { const f32x4 w = *(const LAS f32x4*)(wg + k * 16 + 4 * q);
;                     a0[4 * q] += x0 * w.x; a0[4 * q + 1] += x0 * w.y; a0[4 * q + 2] += x0 * w.z; a0[4 * q + 3] += x0 * w.w;
;                     a1[4 * q] += x1 * w.x; a1[4 * q + 1] += x1 * w.y; a1[4 * q + 2] += x1 * w.z; a1[4 * q + 3] += x1 * w.w; } }
;             float v0 = 0.f, v1 = 0.f;
; #pragma unroll
;             for (int n = 0; n < 16; ++n) { const float s0 = wave_sum(a0[n]), s1 = wave_sum(a1[n]); v0 = (lane == n) ? s0 : v0; v1 = (lane == n) ? s1 : v1; }
;             if (lane < 16) { gl[(wid * 8 + tt) * 16 + lane] = v0; gl[(wid * 8 + tt + 1) * 16 + lane] = v1; }
;         }
.LBB0_142:
	s_or_b64 exec, exec, s[44:45]
	s_add_i32 s1, s1, 2
	s_mov_b64 s[44:45], 0x800
	v_add_u32_e32 v6, 0x80, v6
	v_lshl_add_u64 v[2:3], v[2:3], 0, s[44:45]
	s_cmp_gt_u32 s1, 5
	v_lshl_add_u64 v[4:5], v[4:5], 0, s[62:63]
	s_cbranch_scc1 .LBB0_145
	.p2align 6

; #define LAS __attribute__((address_space(3)))
; DI float logsig(float z) { return fminf(z, 0.f) - __logf(1.f + __expf(-fabsf(z))); }
; DI void gla_gate_phase(int wv, LAS unsigned char* lds, const float* x, const float* w_in, const float* w2, const float* bg, const bf16_t* qk1,
;                        bf16_t* qd, bf16_t* ki, bf16_t* kst, float* decay, bf16_t* sbuf) {
;     ...
;         __syncthreads();
;         float cum = 0.f;
; #pragma unroll 4
;         for (int t = 0; t < 64; ++t) { float z = bc;
; #pragma unroll
;             for (int q = 0; q < 4; ++q) { const f32x4 gv = *(const LAS f32x4*)(gl + t * 16 + 4 * q); z += gv.x * w2c[4 * q] + gv.y * w2c[4 * q + 1] + gv.z * w2c[4 * q + 2] + gv.w * w2c[4 * q + 3]; }
;             cum += logsig(z) * 0.0625f; }
.LBB0_145:
	v_mov_b32_e32 v93, 0
	s_mov_b32 s1, 0
	s_waitcnt lgkmcnt(0)
	s_barrier
	.p2align 6

; DI void gla_scan_phase(int wv, LAS unsigned char* lds, const bf16_t* qd, const bf16_t* kst, const bf16_t* sbuf, const bf16_t* vt, const float* decay, float* obuf) {
;     ...
;         } else if (wid == 4) {
;             const bf16_t* sb0 = sbuf + ((size_t)b * 4 + hd) * 64 * 4096; const unsigned ls = (unsigned)(rr * 64 + 8 * hh);
;             bf16x8 vA[4], sB[6], nvA[4], nsB[6];
;     ...
;             SCAN_LOADI(0, vA, sB);
; #pragma nounroll
;             for (int c = 0; c < 64; c += 2) {
.LBB0_193:
	s_and_b64 vcc, exec, s[18:19]
	s_cbranch_vccz .LBB0_196
	s_lshl_b32 s2, s20, 19
	s_lshl_b64 s[22:23], s[14:15], 21
	v_readlane_b32 s18, v253, 50
	v_readlane_b32 s19, v253, 51
	s_add_u32 s3, s18, s22
	s_addc_u32 s19, s19, s23
	v_lshlrev_b32_e32 v0, 1, v176
	s_add_u32 s18, s3, s2
	v_lshl_add_u64 v[114:115], s[12:13], 0, v[0:1]
	global_load_dwordx4 v[34:37], v0, s[12:13]
	global_load_dwordx4 v[38:41], v0, s[12:13] offset:32
	global_load_dwordx4 v[42:45], v0, s[12:13] offset:64
	global_load_dwordx4 v[46:49], v0, s[12:13] offset:96
	s_addc_u32 s19, s19, 0
	v_lshlrev_b32_e32 v0, 1, v178
	v_lshl_add_u64 v[2:3], s[18:19], 0, v[0:1]
	global_load_dwordx4 v[50:53], v0, s[18:19]
	global_load_dwordx4 v[54:57], v0, s[18:19] offset:32
	v_lshlrev_b32_e32 v0, 1, v180
	v_add_co_u32_e32 v2, vcc, s77, v2
	s_add_u32 s24, s55, s16
	s_nop 0
	v_addc_co_u32_e32 v3, vcc, 0, v3, vcc
	global_load_dwordx4 v[66:69], v0, s[18:19]
	global_load_dwordx4 v[70:73], v[2:3], off offset:32
	global_load_dwordx4 v[74:77], v[2:3], off offset:64
	global_load_dwordx4 v[78:81], v[2:3], off offset:96
	s_addc_u32 s25, 0, s17
	s_or_b32 s22, s22, s2
	v_lshl_add_u64 v[116:117], s[24:25], 0, v[186:187]
	v_lshl_add_u64 v[118:119], s[22:23], 0, v[188:189]
	v_lshl_add_u64 v[120:121], s[22:23], 0, v[190:191]
	s_mov_b32 s21, -2
	.p2align 6

; DI f32x16 zero16() { f32x16 z; for (int i = 0; i < 16; ++i) z[i] = 0.f; return z; }
; DI void gla_scan_phase(int wv, LAS unsigned char* lds, const bf16_t* qd, const bf16_t* kst, const bf16_t* sbuf, const bf16_t* vt, const float* decay, float* obuf) {
;     ...
;         const bf16_t* vrow = vt + (size_t)(hd * 256 + dvs * 32) * M_TOK + (size_t)b * SEQ; const unsigned lv = (unsigned)(rr * M_TOK + 8 * hh);
;         if (wid < 4) {
;             const int kb = wid;
;             f32x16 St = zero16();
;             const bf16_t* krow = kst + ((size_t)b * 512 + hd * 128 + kb * 32) * SEQ; const unsigned lk = (unsigned)(rr * SEQ + 8 * hh);
;             const bf16_t* qp0 = qd + (size_t)b * SEQ * 512 + hd * 128 + kb * 32; const unsigned lq = (unsigned)(rr * 512 + 4 * hh);
;             const float* dp0 = decay + (size_t)b * 64 * 512 + hd * 128 + kb * 32; const unsigned ld_ = (unsigned)(4 * hh);
;             const int qt = wid >> 1;
;             bf16x8 vA[4], kA[4], qB[4]; f32x4 dc[4];
;             bf16x8 nvA[4], nkA[4], nqB[4]; f32x4 ndc[4];
;     ...
;             SCAN_LOADC(0, vA, kA, qB, dc);
; #pragma nounroll
;             for (int c = 0; c < 64; c += 2) {
.LBB0_197:
	s_andn2_b64 vcc, exec, s[18:19]
	s_cbranch_vccnz .LBB0_187
	s_lshr_b32 s2, s82, 5
	s_and_b32 s2, s2, 7
	s_lshl_b64 s[24:25], s[14:15], 12
	s_lshl_b32 s3, s20, 10
	s_lshl_b32 s2, s2, 7
	s_lshl_b32 s68, s20, 7
	s_lshl_b32 s75, s20, 9
	s_lshl_b32 s83, s20, 8
	s_lshl_b64 s[18:19], s[14:15], 9
	s_add_u32 s95, s18, s6
	s_addc_u32 s28, s19, s7
	s_add_u32 s18, s95, s68
	s_addc_u32 s19, s28, 0
	s_lshl_b64 s[18:19], s[18:19], 13
	v_readlane_b32 s20, v253, 48
	s_add_u32 s18, s20, s18
	v_readlane_b32 s20, v253, 49
	s_addc_u32 s19, s20, s19
	s_lshl_b64 s[22:23], s[14:15], 22
	v_readlane_b32 s20, v253, 46
	v_readlane_b32 s21, v253, 47
	s_add_u32 s20, s20, s22
	s_addc_u32 s21, s21, s23
	s_add_u32 s20, s20, s83
	s_addc_u32 s21, s21, 0
	s_lshl_b64 s[26:27], s[14:15], 17
	v_readlane_b32 s56, v253, 52
	s_add_u32 s56, s56, s26
	v_readlane_b32 s94, v253, 53
	s_addc_u32 vcc_lo, s94, s27
	s_add_u32 s56, s56, s75
	s_addc_u32 s94, vcc_lo, 0
	v_lshlrev_b32_e32 v0, 1, v176
	v_mov_b32_e32 v209, v1
	global_load_dwordx4 v[50:53], v0, s[12:13]
	v_lshl_add_u64 v[212:213], s[18:19], 0, v[208:209]
	global_load_dwordx4 v[54:57], v208, s[18:19]
	global_load_dwordx4 v[70:73], v0, s[12:13] offset:32
	global_load_dwordx4 v[66:69], v208, s[18:19] offset:32
	global_load_dwordx4 v[62:65], v0, s[12:13] offset:64
	global_load_dwordx4 v[58:61], v208, s[18:19] offset:64
	global_load_dwordx4 v[110:113], v0, s[12:13] offset:96
	global_load_dwordx4 v[106:109], v208, s[18:19] offset:96
	s_add_u32 s18, s20, s10
	s_addc_u32 s19, s21, s11
	v_lshlrev_b32_e32 v214, 1, v184
	v_mov_b32_e32 v215, v1
	v_lshl_add_u64 v[2:3], s[18:19], 0, v[214:215]
	v_add_co_u32_e32 v2, vcc, s71, v2
	global_load_dwordx2 v[94:95], v214, s[18:19]
	global_load_dwordx2 v[96:97], v214, s[18:19] offset:16
	v_addc_co_u32_e32 v3, vcc, 0, v3, vcc
	global_load_dwordx2 v[102:103], v[2:3], off
	global_load_dwordx2 v[104:105], v[2:3], off offset:16
	global_load_dwordx2 v[90:91], v214, s[18:19] offset:32
	global_load_dwordx2 v[92:93], v214, s[18:19] offset:48
	global_load_dwordx2 v[98:99], v[2:3], off offset:32
	global_load_dwordx2 v[100:101], v[2:3], off offset:48
	s_add_u32 s20, s56, s8
	v_lshl_add_u64 v[210:211], s[12:13], 0, v[0:1]
	s_addc_u32 s21, s94, s9
	v_lshlrev_b32_e32 v0, 2, v182
	global_load_dwordx4 v[74:77], v0, s[20:21]
	global_load_dwordx4 v[78:81], v0, s[20:21] offset:32
	global_load_dwordx4 v[82:85], v0, s[20:21] offset:64
	global_load_dwordx4 v[86:89], v0, s[20:21] offset:96
	s_add_u32 s16, s55, s16
	s_addc_u32 s17, 0, s17
	v_lshl_add_u64 v[2:3], v[196:197], 0, s[24:25]
	s_or_b32 s56, s2, s3
	v_lshlrev_b64 v[2:3], 12, v[2:3]
	s_add_u32 s24, s95, s68
	v_lshl_add_u64 v[2:3], v[194:195], 0, v[2:3]
	s_addc_u32 s25, s28, 0
	s_lshl_b64 s[14:15], s[14:15], 24
	v_lshl_add_u64 v[218:219], s[56:57], 0, v[2:3]
	s_lshl_b64 s[24:25], s[24:25], 13
	s_or_b32 s14, s14, s56
	s_or_b32 s26, s26, s75
	s_or_b32 s22, s22, s83
	v_mov_b32_e32 v2, 0
	s_mov_b32 s94, 0x40000
	v_lshl_add_u64 v[216:217], s[16:17], 0, v[192:193]
	v_lshl_add_u64 v[220:221], v[198:199], 0, s[24:25]
	v_lshl_add_u64 v[222:223], s[14:15], 0, v[200:201]
	v_lshl_add_u64 v[224:225], s[26:27], 0, v[202:203]
	v_lshl_add_u64 v[226:227], s[22:23], 0, v[204:205]
	v_lshl_add_u64 v[228:229], s[16:17], 0, v[186:187]
	v_lshl_add_u64 v[230:231], v[206:207], 0, s[24:25]
	s_mov_b32 s14, -2
	v_mov_b32_e32 v3, v2
	v_mov_b32_e32 v4, v2
	v_mov_b32_e32 v5, v2
	v_mov_b32_e32 v6, v2
	v_mov_b32_e32 v7, v2
	v_mov_b32_e32 v8, v2
	v_mov_b32_e32 v9, v2
	v_mov_b32_e32 v10, v2
	v_mov_b32_e32 v11, v2
	v_mov_b32_e32 v12, v2
	v_mov_b32_e32 v13, v2
	s_waitcnt vmcnt(0)
	v_mov_b32_e32 v14, v2
	v_mov_b32_e32 v15, v2
	v_mov_b32_e32 v16, v2
	v_mov_b32_e32 v17, v2
	.p2align 6

; DI f32x16 zero16() { f32x16 z; for (int i = 0; i < 16; ++i) z[i] = 0.f; return z; }
; DI void dil_attn_phase(int wv, const bf16_t* qk, const bf16_t* vt, float* oacc, float* stats, bf16_t* ob, int g, int dil) {
;     ...
;         const int lt = task % ntl; int t2 = task / ntl; const int head = t2 & 7; t2 >>= 3; const int rph = t2 % dil, b = t2 / dil;
;         const int l0 = lt * 32;
;         const float slope2d = exp2f(-(float)(head + 1)) * LOG2E * (float)dil;
;         const size_t qrow = (size_t)b * SEQ + (size_t)(l0 + rr) * dil + rph;
;         bf16x8 qf[8];
; #pragma unroll
;         for (int ks = 0; ks < 8; ++ks) qf[ks] = *(const bf16x8*)(qk + qrow * 2048 + head * 128 + ks * 16 + hh * 8);
;         f32x16 O[4];
; #pragma unroll
;         for (int d = 0; d < 4; ++d) O[d] = zero16();
;         float m = -INFINITY, l = 0.f;
;         float st_m0 = 0.f, st_l0 = 0.f;
;         if (g > 0) { const float* stp = stats + (qrow * 8 + head) * 2; st_m0 = stp[0]; st_l0 = stp[1]; }
; #pragma nounroll
;         for (int jt = (l0 >= 128) ? 0 : 4 - (l0 >> 5); jt < 5; ++jt) {
;             const int kl0 = l0 - 128 + 32 * jt;
;             const size_t krow = (size_t)b * SEQ + (size_t)(kl0 + prr) * dil + rph;
.LBB0_279:
	s_lshl_b32 s24, s23, 7
	s_sub_i32 s2, 4, s27
	s_cmp_lt_i32 s27, 4
	s_cselect_b32 s27, s2, 0
	v_mov_b32_e32 v67, 0xff800000
	s_cmp_gt_i32 s27, 4
	v_mov_b32_e32 v16, 0
	v_mov_b32_e32 v15, 0
	v_mov_b32_e32 v14, 0
	v_mov_b32_e32 v13, 0
	v_mov_b32_e32 v12, 0
	v_mov_b32_e32 v11, 0
	v_mov_b32_e32 v10, 0
	v_mov_b32_e32 v9, 0
	v_mov_b32_e32 v8, 0
	v_mov_b32_e32 v7, 0
	v_mov_b32_e32 v6, 0
	v_mov_b32_e32 v5, 0
	v_mov_b32_e32 v4, 0
	v_mov_b32_e32 v3, 0
	v_mov_b32_e32 v2, 0
	v_mov_b32_e32 v33, 0
	v_mov_b32_e32 v32, 0
	v_mov_b32_e32 v31, 0
	v_mov_b32_e32 v30, 0
	v_mov_b32_e32 v29, 0
	v_mov_b32_e32 v28, 0
	v_mov_b32_e32 v27, 0
	v_mov_b32_e32 v26, 0
	v_mov_b32_e32 v25, 0
	v_mov_b32_e32 v24, 0
	v_mov_b32_e32 v23, 0
	v_mov_b32_e32 v22, 0
	v_mov_b32_e32 v21, 0
	v_mov_b32_e32 v20, 0
	v_mov_b32_e32 v19, 0
	v_mov_b32_e32 v18, 0
	v_mov_b32_e32 v49, 0
	v_mov_b32_e32 v48, 0
	v_mov_b32_e32 v47, 0
	v_mov_b32_e32 v46, 0
	v_mov_b32_e32 v45, 0
	v_mov_b32_e32 v44, 0
	v_mov_b32_e32 v43, 0
	v_mov_b32_e32 v42, 0
	v_mov_b32_e32 v41, 0
	v_mov_b32_e32 v40, 0
	v_mov_b32_e32 v39, 0
	v_mov_b32_e32 v38, 0
	v_mov_b32_e32 v37, 0
	v_mov_b32_e32 v36, 0
	v_mov_b32_e32 v35, 0
	v_mov_b32_e32 v34, 0
	v_mov_b32_e32 v65, 0
	v_mov_b32_e32 v64, 0
	v_mov_b32_e32 v63, 0
	v_mov_b32_e32 v62, 0
	v_mov_b32_e32 v61, 0
	v_mov_b32_e32 v60, 0
	v_mov_b32_e32 v59, 0
	v_mov_b32_e32 v58, 0
	v_mov_b32_e32 v57, 0
	v_mov_b32_e32 v56, 0
	v_mov_b32_e32 v55, 0
	v_mov_b32_e32 v54, 0
	v_mov_b32_e32 v53, 0
	v_mov_b32_e32 v52, 0
	v_mov_b32_e32 v51, 0
	v_mov_b32_e32 v50, 0
	v_mov_b32_e32 v180, 0
	s_cbranch_scc1 .LBB0_282
	s_add_i32 s2, s23, 1
	v_cvt_f32_ubyte0_e32 v2, s2
	s_mov_b32 s2, 0x42fc0000
	v_cmp_lt_f32_e32 vcc, s2, v2
	s_and_b64 s[28:29], vcc, exec
	s_cselect_b32 s2, 0xffffffc0, 0
	v_cndmask_b32_e32 v3, 0, v247, vcc
	v_sub_f32_e32 v2, v3, v2
	v_exp_f32_e32 v2, v2
	s_lshl_b64 s[12:13], s[12:13], 1
	s_add_u32 s12, s78, s12
	s_addc_u32 s13, s79, s13
	v_ldexp_f32 v2, v2, s2
	v_mul_f32_e32 v2, 0x3fb8aa3b, v2
	v_mul_f32_e32 v159, v2, v147
	v_lshl_or_b32 v2, s23, 23, v179
	v_mov_b32_e32 v3, v1
	v_lshl_add_u64 v[2:3], s[12:13], 0, v[2:3]
	s_lshl_b64 s[10:11], s[10:11], s17
	s_lshl_b32 s12, s27, 5
	s_lshl_b32 s2, s14, 5
	v_lshl_add_u64 v[2:3], s[10:11], 1, v[2:3]
	s_add_i32 s2, s12, s2
	v_mov_b32_e32 v180, 0
	v_lshl_add_u64 v[160:161], v[2:3], 0, v[0:1]
	s_lshl_b32 s56, s24, 1
	v_add_u32_e32 v2, s2, v178
	s_mul_i32 s2, s22, s26
	v_lshl_add_u64 v[162:163], v[148:149], 0, s[56:57]
	s_ashr_i32 s10, s25, 31
	s_add_i32 s11, s27, -1
	v_subrev_u32_e32 v181, s12, v177
	v_subrev_u32_e32 v164, s2, v2
	v_mov_b32_e32 v67, 0xff800000
	v_mov_b32_e32 v50, 0
	v_mov_b32_e32 v51, v180
	v_mov_b32_e32 v52, v180
	v_mov_b32_e32 v53, v180
	v_mov_b32_e32 v54, v180
	v_mov_b32_e32 v55, v180
	v_mov_b32_e32 v56, v180
	v_mov_b32_e32 v57, v180
	v_mov_b32_e32 v58, v180
	v_mov_b32_e32 v59, v180
	v_mov_b32_e32 v60, v180
	v_mov_b32_e32 v61, v180
	v_mov_b32_e32 v62, v180
	v_mov_b32_e32 v63, v180
	v_mov_b32_e32 v64, v180
	v_mov_b32_e32 v65, v180
	v_mov_b32_e32 v34, 0
	v_mov_b32_e32 v35, v180
	v_mov_b32_e32 v36, v180
	v_mov_b32_e32 v37, v180
	v_mov_b32_e32 v38, v180
	v_mov_b32_e32 v39, v180
	v_mov_b32_e32 v40, v180
	v_mov_b32_e32 v41, v180
	v_mov_b32_e32 v42, v180
	v_mov_b32_e32 v43, v180
	v_mov_b32_e32 v44, v180
	v_mov_b32_e32 v45, v180
	v_mov_b32_e32 v46, v180
	v_mov_b32_e32 v47, v180
	v_mov_b32_e32 v48, v180
	v_mov_b32_e32 v49, v180
	v_mov_b32_e32 v18, 0
	v_mov_b32_e32 v19, v180
	v_mov_b32_e32 v20, v180
	v_mov_b32_e32 v21, v180
	v_mov_b32_e32 v22, v180
	v_mov_b32_e32 v23, v180
	v_mov_b32_e32 v24, v180
	v_mov_b32_e32 v25, v180
	v_mov_b32_e32 v26, v180
	v_mov_b32_e32 v27, v180
	v_mov_b32_e32 v28, v180
	v_mov_b32_e32 v29, v180
	v_mov_b32_e32 v30, v180
	v_mov_b32_e32 v31, v180
	v_mov_b32_e32 v32, v180
	v_mov_b32_e32 v33, v180
	v_mov_b32_e32 v2, 0
	v_mov_b32_e32 v3, v180
	v_mov_b32_e32 v4, v180
	v_mov_b32_e32 v5, v180
	v_mov_b32_e32 v6, v180
	v_mov_b32_e32 v7, v180
	v_mov_b32_e32 v8, v180
	v_mov_b32_e32 v9, v180
	v_mov_b32_e32 v10, v180
	v_mov_b32_e32 v11, v180
	v_mov_b32_e32 v12, v180
	v_mov_b32_e32 v13, v180
	v_mov_b32_e32 v14, v180
	v_mov_b32_e32 v15, v180
	v_mov_b32_e32 v16, v180
	v_mov_b32_e32 v17, v180
	.p2align 6
